# one static s_setprio 1 for waves 4-7 at kernel entry, GEMM per-segment priority flips deleted
# baseline (speedup 1.0000x reference)
_Z8mega_fwd4Args:
	s_mov_b32 s65, s2
	s_add_u32 s2, s0, 0xe8
	s_addc_u32 s3, s1, 0
	v_readfirstlane_b32 s97, v0
	v_writelane_b32 v254, s2, 0
	s_nop 3
	s_cmpk_ge_u32 s97, 0x100
	s_cbranch_scc0 .Lprio_skip
	s_setprio 1
.Lprio_skip:
	v_cmp_gt_u32_e32 vcc, 64, v0
	s_nop 0
	v_writelane_b32 v254, s3, 1
	s_and_saveexec_b64 s[4:5], vcc
	v_lshl_add_u32 v1, v0, 2, 0
	v_add_u32_e32 v1, 0x23f00, v1
	v_mov_b32_e32 v2, 0
	ds_write_b32 v1, v2
	s_or_b64 exec, exec, s[4:5]
	s_load_dword s3, s[0:1], 0xe8
	s_waitcnt lgkmcnt(0)
	s_barrier
	s_getreg_b32 s2, hwreg(HW_REG_XCC_ID, 0, 4)
	s_mov_b32 s33, 0
	v_cmp_eq_u32_e32 vcc, 0, v0
	s_and_saveexec_b64 s[4:5], vcc
	s_cbranch_execz .LBB0_5
	s_mov_b64 s[6:7], exec
	v_mbcnt_lo_u32_b32 v0, s6, 0
	v_mbcnt_hi_u32_b32 v0, s7, v0
	v_cmp_eq_u32_e32 vcc, 0, v0
	s_and_b64 s[8:9], exec, vcc
	s_mov_b64 exec, s[8:9]
	s_cbranch_execz .LBB0_5
	s_load_dwordx2 s[8:9], s[0:1], 0xe0
	s_lshl_b32 s2, s2, 8
	s_and_b32 s2, s2, 0xf00
	v_mov_b32_e32 v0, 0x4000
	s_waitcnt lgkmcnt(0)
	s_add_u32 s8, s8, s2
	s_addc_u32 s9, s9, 0
	s_bcnt1_i32_b64 s2, s[6:7]
	v_mov_b32_e32 v1, s2
	global_atomic_add v0, v1, s[8:9] offset:1024
